# XCD-local FF1-to-FF2 seam plus all prologue stores write-through with the L2 write-back dropped at the two prologue seams, final norm stores write-through
# baseline (speedup 1.0000x reference)
.LBB0_19:
	s_or_b64 exec, exec, s[0:1]
	s_waitcnt lgkmcnt(0)
	s_barrier
	s_and_saveexec_b64 s[0:1], s[4:5]
	s_cbranch_execz .LBB0_14
	s_mul_i32 s12, s38, 0x1800
	s_add_i32 s12, s12, s10
	v_or_b32_e32 v10, s12, v50
	v_readlane_b32 s48, v252, 3
	v_ashrrev_i32_e32 v11, 31, v10
	v_readlane_b32 s62, v252, 17
	v_readlane_b32 s63, v252, 18
	v_mad_i64_i32 v[18:19], s[12:13], s38, 6, v[6:7]
	s_nop 0
	v_lshl_add_u64 v[10:11], v[10:11], 2, s[62:63]
	global_load_dword v22, v[10:11], off
	ds_read2st64_b32 v[10:11], v62 offset0:96 offset1:102
	ds_read2st64_b32 v[12:13], v62 offset0:108 offset1:114
	ds_read2st64_b32 v[14:15], v62 offset0:120 offset1:126
	ds_read2st64_b32 v[16:17], v62 offset0:132 offset1:138
	v_mov_b64_e32 v[20:21], s[8:9]
	s_waitcnt lgkmcnt(3)
	v_add_f32_e32 v10, 0, v10
	v_add_f32_e32 v10, v10, v11
	s_waitcnt lgkmcnt(2)
	v_add_f32_e32 v10, v10, v12
	v_add_f32_e32 v10, v10, v13
	s_waitcnt lgkmcnt(1)
	v_add_f32_e32 v10, v10, v14
	v_mad_u64_u32 v[20:21], s[12:13], v18, s14, v[20:21]
	v_add_f32_e32 v10, v10, v15
	v_mad_i32_i24 v21, v19, s14, v21
	s_waitcnt lgkmcnt(0)
	v_add_f32_e32 v10, v10, v16
	v_lshl_add_u64 v[18:19], s[10:11], 2, v[20:21]
	v_add_f32_e32 v10, v10, v17
	v_readlane_b32 s49, v252, 4
	v_readlane_b32 s50, v252, 5
	v_readlane_b32 s51, v252, 6
	v_readlane_b32 s52, v252, 7
	v_readlane_b32 s53, v252, 8
	v_readlane_b32 s54, v252, 9
	v_readlane_b32 s55, v252, 10
	v_readlane_b32 s56, v252, 11
	v_readlane_b32 s57, v252, 12
	v_readlane_b32 s58, v252, 13
	v_readlane_b32 s59, v252, 14
	v_readlane_b32 s60, v252, 15
	v_readlane_b32 s61, v252, 16
	s_waitcnt vmcnt(0)
	v_add_f32_e32 v12, v10, v22
	v_lshl_add_u64 v[10:11], v[18:19], 0, v[4:5]
	global_store_dword v[10:11], v12, off sc1
	s_branch .LBB0_14

.LBB0_40:
	v_ashrrev_i32_e32 v3, 6, v7
	v_ashrrev_i32_e32 v51, 6, v6
	v_ashrrev_i32_e32 v52, 6, v5
	v_ashrrev_i32_e32 v53, 6, v4
	v_mul_hi_i32 v26, v53, s45
	v_mul_hi_i32 v27, v52, s45
	v_mul_hi_i32 v28, v51, s45
	v_mul_hi_i32 v29, v3, s45
	v_lshrrev_b32_e32 v30, 31, v26
	v_lshrrev_b32_e32 v26, 3, v26
	v_lshrrev_b32_e32 v31, 31, v27
	v_lshrrev_b32_e32 v27, 3, v27
	v_lshrrev_b32_e32 v32, 31, v28
	v_lshrrev_b32_e32 v28, 3, v28
	v_lshrrev_b32_e32 v33, 31, v29
	v_lshrrev_b32_e32 v29, 3, v29
	v_add_u32_e32 v26, v26, v30
	v_add_u32_e32 v27, v27, v31
	v_add_u32_e32 v28, v28, v32
	v_add_u32_e32 v29, v29, v33
	v_lshl_add_u32 v26, v26, 4, v53
	v_lshl_add_u32 v27, v27, 4, v52
	v_lshl_add_u32 v28, v28, 4, v51
	v_lshl_add_u32 v29, v29, 4, v3
	v_mul_lo_u32 v29, v29, v7
	v_mul_lo_u32 v28, v28, v6
	v_mul_lo_u32 v27, v27, v5
	v_mul_lo_u32 v26, v26, v4
	v_and_b32_e32 v30, 63, v26
	v_and_b32_e32 v31, 63, v27
	v_and_b32_e32 v26, 63, v28
	v_and_b32_e32 v27, 63, v29
	v_cvt_f32_ubyte0_e32 v27, v27
	v_cvt_f32_ubyte0_e32 v26, v26
	v_cvt_f32_ubyte0_e32 v29, v31
	v_cvt_f32_ubyte0_e32 v28, v30
	v_pk_mul_f32 v[28:29], v[28:29], s[36:37] op_sel_hi:[1,0]
	v_pk_mul_f32 v[26:27], v[26:27], s[36:37] op_sel_hi:[1,0]
	v_add_u32_e32 v17, -4, v17
	v_pk_mul_f32 v[30:31], v[26:27], 0.5 op_sel_hi:[1,0]
	v_pk_mul_f32 v[32:33], v[28:29], 0.5 op_sel_hi:[1,0]
	v_cmp_eq_u32_e32 vcc, 0, v17
	v_fract_f32_e32 v34, v32
	v_fract_f32_e32 v35, v33
	v_fract_f32_e32 v36, v30
	v_fract_f32_e32 v37, v31
	s_or_b64 s[34:35], vcc, s[34:35]
	v_pk_add_f32 v[36:37], v[36:37], v[36:37]
	v_pk_add_f32 v[34:35], v[34:35], v[34:35]
	v_cmp_neq_f32_e32 vcc, s53, v33
	v_cmp_neq_f32_e64 s[0:1], s53, v30
	v_cmp_neq_f32_e64 s[4:5], s53, v31
	v_cmp_neq_f32_e64 s[8:9], s53, v32
	v_cndmask_b32_e32 v33, 0, v35, vcc
	v_cndmask_b32_e64 v30, 0, v36, s[0:1]
	v_cndmask_b32_e64 v32, 0, v34, s[8:9]
	v_cndmask_b32_e64 v31, 0, v37, s[4:5]
	v_cmp_lt_f32_e32 vcc, 1.0, v28
	v_cmp_lt_f32_e64 s[0:1], 1.0, v29
	v_cmp_lt_f32_e64 s[4:5], 1.0, v26
	v_cmp_lt_f32_e64 s[8:9], 1.0, v27
	v_cndmask_b32_e64 v33, v29, v33, s[0:1]
	v_cndmask_b32_e64 v30, v26, v30, s[4:5]
	v_cndmask_b32_e64 v31, v27, v31, s[8:9]
	v_cndmask_b32_e32 v32, v28, v32, vcc
	v_pk_add_f32 v[34:35], v[32:33], v[32:33]
	v_pk_add_f32 v[36:37], v[30:31], v[30:31]
	v_rndne_f32_e32 v35, v35
	v_rndne_f32_e32 v37, v37
	v_rndne_f32_e32 v36, v36
	v_rndne_f32_e32 v34, v34
	v_pk_fma_f32 v[32:33], v[34:35], -0.5, v[32:33] op_sel_hi:[1,0,1]
	v_pk_fma_f32 v[30:31], v[36:37], -0.5, v[30:31] op_sel_hi:[1,0,1]
	v_cvt_i32_f32_e32 v54, v34
	v_cvt_i32_f32_e32 v55, v35
	v_cvt_i32_f32_e32 v56, v36
	v_cvt_i32_f32_e32 v57, v37
	v_pk_mul_f32 v[34:35], v[30:31], v[30:31]
	v_pk_mul_f32 v[36:37], v[32:33], v[32:33]
	v_pk_fma_f32 v[40:41], v[34:35], s[38:39], v[8:9] op_sel_hi:[1,0,0]
	v_pk_fma_f32 v[38:39], v[36:37], s[38:39], v[8:9] op_sel_hi:[1,0,0]
	v_pk_fma_f32 v[46:47], v[36:37], s[52:53], v[10:11] op_sel_hi:[1,0,0]
	v_pk_fma_f32 v[48:49], v[34:35], s[52:53], v[10:11] op_sel_hi:[1,0,0]
	v_pk_fma_f32 v[40:41], v[34:35], v[40:41], s[40:41] op_sel_hi:[1,1,0]
	v_pk_fma_f32 v[38:39], v[36:37], v[38:39], s[40:41] op_sel_hi:[1,1,0]
	v_pk_fma_f32 v[48:49], v[34:35], v[48:49], s[54:55] op_sel_hi:[1,1,0]
	v_pk_fma_f32 v[46:47], v[36:37], v[46:47], s[54:55] op_sel_hi:[1,1,0]
	v_pk_mul_f32 v[42:43], v[32:33], v[36:37]
	v_pk_mul_f32 v[44:45], v[30:31], v[34:35]
	v_pk_fma_f32 v[38:39], v[36:37], v[38:39], s[42:43] op_sel_hi:[1,1,0]
	v_pk_fma_f32 v[40:41], v[34:35], v[40:41], s[42:43] op_sel_hi:[1,1,0]
	v_pk_fma_f32 v[46:47], v[36:37], v[46:47], s[60:61] op_sel_hi:[1,1,0]
	v_pk_fma_f32 v[48:49], v[34:35], v[48:49], s[60:61] op_sel_hi:[1,1,0]
	v_and_b32_e32 v58, 1, v57
	v_and_b32_e32 v59, 1, v56
	v_and_b32_e32 v60, 1, v55
	v_and_b32_e32 v61, 1, v54
	v_pk_mul_f32 v[40:41], v[44:45], v[40:41]
	v_pk_mul_f32 v[38:39], v[42:43], v[38:39]
	v_pk_fma_f32 v[42:43], v[34:35], v[48:49], s[62:63] op_sel_hi:[1,1,0]
	v_pk_fma_f32 v[44:45], v[36:37], v[46:47], s[62:63] op_sel_hi:[1,1,0]
	v_lshlrev_b32_e32 v62, 30, v57
	v_lshlrev_b32_e32 v63, 30, v56
	v_lshlrev_b32_e32 v64, 30, v55
	v_lshlrev_b32_e32 v65, 30, v54
	v_and_b32_e32 v54, 2, v54
	v_and_b32_e32 v55, 2, v55
	v_and_b32_e32 v56, 2, v56
	v_and_b32_e32 v57, 2, v57
	v_pk_fma_f32 v[32:33], v[32:33], s[44:45], v[38:39] op_sel_hi:[1,0,1]
	v_pk_fma_f32 v[30:31], v[30:31], s[44:45], v[40:41] op_sel_hi:[1,0,1]
	v_pk_fma_f32 v[36:37], v[36:37], v[44:45], 1.0 op_sel_hi:[1,1,0]
	v_pk_fma_f32 v[34:35], v[34:35], v[42:43], 1.0 op_sel_hi:[1,1,0]
	v_cmp_eq_u32_e32 vcc, 0, v61
	v_cmp_eq_u32_e64 s[0:1], 0, v60
	v_cmp_eq_u32_e64 s[4:5], 0, v59
	v_cmp_eq_u32_e64 s[8:9], 0, v58
	v_cndmask_b32_e64 v40, v37, v33, s[0:1]
	v_cndmask_b32_e64 v39, v34, v30, s[4:5]
	v_cndmask_b32_e64 v38, v35, v31, s[8:9]
	v_cndmask_b32_e32 v41, v36, v32, vcc
	v_cndmask_b32_e64 v31, -v31, v35, s[8:9]
	v_cndmask_b32_e64 v30, -v30, v34, s[4:5]
	v_cndmask_b32_e64 v33, -v33, v37, s[0:1]
	v_cndmask_b32_e64 v32, -v32, v36, vcc
	v_cmp_eq_u32_e32 vcc, 0, v57
	v_cmp_eq_u32_e64 s[0:1], 0, v56
	v_cmp_eq_u32_e64 s[4:5], 0, v55
	v_cmp_eq_u32_e64 s[8:9], 0, v54
	v_bitop3_b32 v34, v65, v41, s55 bitop3:0x6c
	v_cmp_lg_f32_e64 s[10:11], s53, v28
	v_bitop3_b32 v28, v64, v40, s55 bitop3:0x6c
	v_cmp_lg_f32_e64 s[12:13], s53, v29
	v_bitop3_b32 v29, v63, v39, s55 bitop3:0x6c
	v_cmp_lg_f32_e64 s[14:15], s53, v26
	v_bitop3_b32 v26, v62, v38, s55 bitop3:0x6c
	v_cndmask_b32_e64 v32, -v32, v32, s[8:9]
	v_cndmask_b32_e64 v33, -v33, v33, s[4:5]
	v_cndmask_b32_e64 v30, -v30, v30, s[0:1]
	v_cndmask_b32_e64 v31, -v31, v31, vcc
	v_cmp_lg_f32_e32 vcc, s53, v27
	v_cndmask_b32_e64 v28, v15, -v28, s[12:13]
	v_cmp_gt_i32_e64 s[4:5], 48, v52
	v_cndmask_b32_e64 v26, v15, -v26, vcc
	v_cndmask_b32_e32 v27, v16, v31, vcc
	v_cmp_gt_i32_e32 vcc, 48, v3
	v_cndmask_b32_e64 v3, v15, -v29, s[14:15]
	v_cndmask_b32_e64 v29, v16, v30, s[14:15]
	v_cndmask_b32_e64 v30, v16, v33, s[12:13]
	v_cndmask_b32_e64 v31, v15, -v34, s[10:11]
	v_cndmask_b32_e64 v32, v16, v32, s[10:11]
	v_cmp_gt_i32_e64 s[8:9], 48, v53
	v_ashrrev_i32_e32 v25, 31, v4
	v_mov_b32_e32 v24, v4
	v_cmp_gt_i32_e64 s[0:1], 48, v51
	v_cndmask_b32_e64 v31, v31, v32, s[8:9]
	v_cndmask_b32_e64 v28, v28, v30, s[4:5]
	v_ashrrev_i32_e32 v19, 31, v7
	v_mov_b32_e32 v18, v7
	v_ashrrev_i32_e32 v21, 31, v6
	v_mov_b32_e32 v20, v6
	v_ashrrev_i32_e32 v23, 31, v5
	v_mov_b32_e32 v22, v5
	v_lshl_add_u64 v[24:25], v[24:25], 1, s[30:31]
	v_add_u32_e32 v7, s43, v7
	v_add_u32_e32 v6, s41, v6
	v_add_u32_e32 v5, s39, v5
	v_add_u32_e32 v4, s19, v4
	v_cndmask_b32_e64 v3, v3, v29, s[0:1]
	v_cndmask_b32_e32 v26, v26, v27, vcc
	v_cvt_pk_bf16_f32 v27, v28, s0
	v_cvt_pk_bf16_f32 v28, v31, s0
	v_lshl_add_u64 v[22:23], v[22:23], 1, s[30:31]
	v_lshl_add_u64 v[20:21], v[20:21], 1, s[30:31]
	v_lshl_add_u64 v[18:19], v[18:19], 1, s[30:31]
	v_cvt_pk_bf16_f32 v26, v26, s0
	v_cvt_pk_bf16_f32 v3, v3, s0
	global_store_short v[24:25], v28, off sc1
	global_store_short v[22:23], v27, off sc1
	global_store_short v[20:21], v3, off sc1
	global_store_short v[18:19], v26, off sc1
	s_andn2_b64 exec, exec, s[34:35]
	s_cbranch_execnz .LBB0_40
	s_or_b64 exec, exec, s[34:35]
	v_mad_u64_u32 v[2:3], s[0:1], v14, s50, v[2:3]
	v_cmp_ne_u32_e32 vcc, v13, v14
	s_orn2_b64 s[0:1], vcc, exec

.LBB0_44:
	s_or_b64 exec, exec, s[10:11]
	v_add_u32_e32 v2, s50, v2
	v_cvt_pk_bf16_f32 v9, v15, s0
	v_cmp_lt_i32_e32 vcc, s15, v2
	global_store_short v[4:5], v9, off sc1
	s_or_b64 s[8:9], vcc, s[8:9]
	v_lshl_add_u64 v[4:5], v[4:5], 0, s[4:5]
	s_andn2_b64 exec, exec, s[8:9]
	s_cbranch_execz .LBB0_49

.LBB0_51:
	v_lshrrev_b32_e32 v9, 7, v2
	v_mul_lo_u32 v10, v9, v2
	v_and_b32_e32 v10, 0x7f, v10
	v_cvt_f32_ubyte0_e32 v10, v10
	v_add_co_u32_e32 v8, vcc, 0x8000, v4
	v_mul_f32_e32 v10, 0x3c800000, v10
	s_nop 0
	v_addc_co_u32_e32 v9, vcc, 0, v5, vcc
	v_add_u32_e32 v2, s50, v2
	v_mul_f32_e32 v11, 0.5, v10
	v_cmp_lt_i32_e32 vcc, s12, v2
	v_fract_f32_e32 v13, v11
	s_or_b64 s[8:9], vcc, s[8:9]
	v_add_f32_e32 v13, v13, v13
	v_cmp_neq_f32_e32 vcc, s10, v11
	s_nop 1
	v_cndmask_b32_e32 v11, 0, v13, vcc
	v_cmp_lt_f32_e32 vcc, 1.0, v10
	s_nop 1
	v_cndmask_b32_e32 v11, v10, v11, vcc
	v_add_f32_e32 v13, v11, v11
	v_rndne_f32_e32 v13, v13
	v_fmac_f32_e32 v11, -0.5, v13
	v_cvt_i32_f32_e32 v13, v13
	v_mul_f32_e32 v14, v11, v11
	v_fmamk_f32 v15, v14, 0x3e75aa41, v3
	v_fmamk_f32 v17, v14, 0x3d4be544, v6
	v_fmaak_f32 v15, v14, v15, 0x40234736
	v_fmaak_f32 v17, v14, v17, 0xbfaad1da
	v_mul_f32_e32 v16, v11, v14
	v_fmaak_f32 v15, v14, v15, 0xc0a55e0e
	v_fmaak_f32 v17, v14, v17, 0x4081e0d3
	v_and_b32_e32 v19, 1, v13
	v_mul_f32_e32 v15, v16, v15
	v_fmaak_f32 v16, v14, v17, 0xc09de9e6
	v_and_b32_e32 v18, 2, v13
	v_fmac_f32_e32 v15, 0x40490fdb, v11
	v_fma_f32 v11, v14, v16, 1.0
	v_cmp_eq_u32_e32 vcc, 0, v19
	v_lshlrev_b32_e32 v13, 30, v13
	s_nop 0
	v_cndmask_b32_e64 v14, -v15, v11, vcc
	v_cndmask_b32_e32 v11, v11, v15, vcc
	v_cmp_eq_u32_e32 vcc, 0, v18
	v_bitop3_b32 v11, v13, v11, s11 bitop3:0x6c
	s_nop 0
	v_cndmask_b32_e64 v14, -v14, v14, vcc
	v_cmp_lg_f32_e32 vcc, s10, v10
	s_nop 1
	v_cndmask_b32_e32 v10, v7, v14, vcc
	v_cndmask_b32_e32 v11, v7, v11, vcc
	v_cvt_pk_bf16_f32 v10, v10, s0
	v_cvt_pk_bf16_f32 v11, v11, s0
	global_store_short v[4:5], v10, off sc1
	global_store_short v[8:9], v11, off sc1
	v_lshl_add_u64 v[4:5], v[4:5], 0, s[4:5]
	s_andn2_b64 exec, exec, s[8:9]
	s_cbranch_execnz .LBB0_51

.LBB0_62:
	v_mul_f32_e32 v2, 0x3e000000, v31
	v_cvt_pk_bf16_f32 v10, v2, s0
	v_lshl_add_u64 v[8:9], v[4:5], 0, v[8:9]
	v_lshlrev_b32_e32 v2, 7, v25
	v_lshl_add_u64 v[8:9], v[8:9], 0, v[2:3]
	v_lshrrev_b32_e32 v2, 5, v13
	v_add_u32_e32 v13, s50, v13
	v_and_b32_e32 v2, 0x7e, v2
	v_cmp_lt_i32_e32 vcc, s11, v13
	v_lshl_add_u64 v[8:9], v[8:9], 0, v[2:3]
	s_or_b64 s[4:5], vcc, s[4:5]
	global_store_short v[8:9], v10, off sc1
	s_andn2_b64 exec, exec, s[4:5]
	s_cbranch_execz .LBB0_129

.LBB0_131:
	s_or_b64 exec, exec, s[8:9]
	v_add_u32_e32 v2, s50, v2
	v_cvt_pk_bf16_f32 v3, v9, s0
	v_cmp_lt_i32_e32 vcc, s12, v2
	global_store_short v[6:7], v3, off sc1
	s_or_b64 s[6:7], vcc, s[6:7]
	v_lshl_add_u64 v[6:7], v[6:7], 0, s[4:5]
	s_andn2_b64 exec, exec, s[6:7]
	s_cbranch_execz .LBB0_136

.LBB0_138:
	v_lshl_add_u64 v[8:9], s[88:89], 0, v[4:5]
	global_load_dword v7, v[8:9], off
	v_add_u32_e32 v2, s50, v2
	v_cmp_lt_i32_e32 vcc, s22, v2
	s_or_b64 s[8:9], vcc, s[8:9]
	v_lshl_add_u64 v[8:9], s[4:5], 0, v[4:5]
	v_lshl_add_u64 v[4:5], v[4:5], 0, s[6:7]
	s_waitcnt vmcnt(0)
	v_mul_f32_e32 v10, 0xbfb8aa3b, v7
	v_fma_f32 v11, v7, s10, -v10
	v_rndne_f32_e32 v12, v10
	v_fmac_f32_e32 v11, 0xb2a5705f, v7
	v_sub_f32_e32 v10, v10, v12
	v_add_f32_e32 v10, v10, v11
	v_cvt_i32_f32_e32 v12, v12
	v_exp_f32_e32 v10, v10
	v_cmp_nlt_f32_e32 vcc, s11, v7
	v_ldexp_f32 v10, v10, v12
	s_nop 0
	v_cndmask_b32_e32 v10, 0, v10, vcc
	v_cmp_ngt_f32_e32 vcc, s12, v7
	s_nop 1
	v_cndmask_b32_e32 v24, v1, v10, vcc
	v_add_f32_e32 v7, 1.0, v24
	v_add_f32_e32 v12, -1.0, v7
	v_frexp_mant_f32_e32 v13, v7
	v_cvt_f64_f32_e32 v[10:11], v7
	v_sub_f32_e32 v14, v12, v7
	v_frexp_exp_i32_f64_e32 v10, v[10:11]
	v_cmp_gt_f32_e32 vcc, s14, v13
	v_sub_f32_e32 v12, v24, v12
	v_add_f32_e32 v11, 1.0, v14
	v_subbrev_co_u32_e32 v10, vcc, 0, v10, vcc
	v_add_f32_e32 v11, v12, v11
	v_sub_u32_e32 v12, 0, v10
	v_ldexp_f32 v7, v7, v12
	v_ldexp_f32 v11, v11, v12
	v_add_f32_e32 v12, -1.0, v7
	v_add_f32_e32 v14, 1.0, v7
	v_add_f32_e32 v13, 1.0, v12
	v_add_f32_e32 v15, -1.0, v14
	v_sub_f32_e32 v13, v7, v13
	v_sub_f32_e32 v7, v7, v15
	v_add_f32_e32 v7, v11, v7
	v_add_f32_e32 v15, v11, v13
	v_add_f32_e32 v11, v14, v7
	v_rcp_f32_e32 v18, v11
	v_add_f32_e32 v13, v12, v15
	v_sub_f32_e32 v14, v14, v11
	v_add_f32_e32 v7, v7, v14
	v_mul_f32_e32 v20, v13, v18
	v_mul_f32_e32 v14, v11, v20
	v_fma_f32 v16, v20, v11, -v14
	v_sub_f32_e32 v12, v12, v13
	v_fmac_f32_e32 v16, v20, v7
	v_add_f32_e32 v19, v15, v12
	v_add_f32_e32 v12, v14, v16
	v_sub_f32_e32 v15, v13, v12
	v_mov_b32_e32 v17, v12
	v_pk_add_f32 v[12:13], v[12:13], v[14:15] neg_lo:[0,1] neg_hi:[0,1]
	v_cvt_f32_i32_e32 v10, v10
	v_pk_add_f32 v[12:13], v[12:13], v[16:17] neg_lo:[0,1] neg_hi:[0,1]
	v_cmp_neq_f32_e32 vcc, s13, v24
	v_add_f32_e32 v13, v19, v13
	v_add_f32_e32 v12, v12, v13
	v_add_f32_e32 v13, v15, v12
	v_mul_f32_e32 v17, v18, v13
	v_mul_f32_e32 v14, v11, v17
	v_fma_f32 v16, v17, v11, -v14
	v_sub_f32_e32 v15, v15, v13
	v_fmac_f32_e32 v16, v17, v7
	v_add_f32_e32 v19, v12, v15
	v_add_f32_e32 v21, v20, v17
	v_add_f32_e32 v12, v14, v16
	v_sub_f32_e32 v11, v21, v20
	v_sub_f32_e32 v15, v13, v12
	v_sub_f32_e32 v7, v17, v11
	v_mov_b32_e32 v17, v12
	v_pk_add_f32 v[12:13], v[12:13], v[14:15] neg_lo:[0,1] neg_hi:[0,1]
	s_nop 0
	v_pk_add_f32 v[12:13], v[12:13], v[16:17] neg_lo:[0,1] neg_hi:[0,1]
	s_nop 0
	v_add_f32_e32 v11, v19, v13
	v_add_f32_e32 v11, v12, v11
	v_add_f32_e32 v11, v15, v11
	v_mul_f32_e32 v11, v18, v11
	v_add_f32_e32 v7, v7, v11
	v_add_f32_e32 v11, v21, v7
	v_mul_f32_e32 v12, v11, v11
	v_sub_f32_e32 v14, v11, v21
	v_fmamk_f32 v15, v12, 0x3e9b6dac, v3
	v_ldexp_f32 v13, v11, 1
	v_sub_f32_e32 v14, v7, v14
	v_mul_f32_e32 v11, v11, v12
	v_fmaak_f32 v7, v12, v15, 0x3f2aaada
	v_ldexp_f32 v17, v14, 1
	v_pk_mul_f32 v[14:15], v[10:11], v[6:7]
	s_nop 0
	v_fma_f32 v12, v10, s15, -v14
	v_fmac_f32_e32 v12, 0xb102e308, v10
	v_pk_add_f32 v[10:11], v[14:15], v[12:13]
	v_mov_b32_e32 v16, v14
	v_sub_f32_e32 v7, v11, v13
	v_sub_f32_e32 v7, v15, v7
	v_add_f32_e32 v17, v17, v7
	v_pk_add_f32 v[18:19], v[10:11], v[14:15] neg_lo:[0,1] neg_hi:[0,1]
	v_pk_add_f32 v[14:15], v[10:11], v[16:17]
	v_mov_b32_e32 v13, v10
	v_mov_b32_e32 v19, v15
	v_pk_add_f32 v[22:23], v[12:13], v[18:19] neg_lo:[0,1] neg_hi:[0,1]
	v_pk_add_f32 v[12:13], v[12:13], v[18:19]
	v_mov_b32_e32 v21, v10
	v_pk_add_f32 v[18:19], v[12:13], v[10:11] op_sel:[1,0] op_sel_hi:[0,1] neg_lo:[0,1] neg_hi:[0,1]
	v_mov_b32_e32 v20, v17
	v_mov_b32_e32 v16, v15
	v_mov_b32_e32 v17, v13
	v_pk_mov_b32 v[10:11], v[10:11], v[18:19] op_sel:[1,0]
	v_pk_add_f32 v[14:15], v[14:15], v[18:19] op_sel_hi:[1,0] neg_lo:[0,1] neg_hi:[0,1]
	v_pk_add_f32 v[10:11], v[16:17], v[10:11] neg_lo:[0,1] neg_hi:[0,1]
	v_mov_b32_e32 v14, v22
	v_pk_add_f32 v[10:11], v[20:21], v[10:11] neg_lo:[0,1] neg_hi:[0,1]
	v_mov_b32_e32 v23, v13
	v_pk_add_f32 v[14:15], v[14:15], v[10:11]
	s_nop 0
	v_pk_add_f32 v[16:17], v[14:15], v[14:15] op_sel:[0,1] op_sel_hi:[1,0]
	s_nop 0
	v_pk_add_f32 v[12:13], v[12:13], v[16:17] op_sel:[1,0] op_sel_hi:[0,1]
	v_mov_b32_e32 v15, v12
	v_mov_b32_e32 v11, v16
	v_pk_add_f32 v[16:17], v[14:15], v[22:23] neg_lo:[0,1] neg_hi:[0,1]
	s_nop 0
	v_sub_f32_e32 v7, v14, v16
	v_pk_add_f32 v[10:11], v[10:11], v[16:17] neg_lo:[0,1] neg_hi:[0,1]
	v_sub_f32_e32 v7, v22, v7
	v_add_f32_e32 v7, v10, v7
	v_add_f32_e32 v7, v7, v11
	v_add_f32_e32 v7, v12, v7
	v_cndmask_b32_e32 v7, v1, v7, vcc
	v_cmp_lt_f32_e64 vcc, |v24|, s19
	s_nop 1
	v_cndmask_b32_e32 v7, v7, v24, vcc
	v_mul_f32_e32 v7, 0xc1000000, v7
	v_mul_f32_e32 v7, 0x3fb8aa3b, v7
	global_store_dword v[8:9], v7, off sc1
	s_andn2_b64 exec, exec, s[8:9]
	s_cbranch_execnz .LBB0_138

.LBB0_142:
	s_add_i32 s14, s16, 0xffffbfff
	s_add_u32 s19, s16, -1
	v_readlane_b32 s48, v252, 3
	s_addc_u32 s15, s17, -1
	v_readlane_b32 s50, v252, 5
	v_readlane_b32 s51, v252, 6
	v_readlane_b32 s52, v252, 7
	v_readlane_b32 s53, v252, 8
	v_readlane_b32 s54, v252, 9
	v_readlane_b32 s55, v252, 10
	s_cmpk_lt_i32 s6, 0x4000
	v_readlane_b32 s49, v252, 4
	s_mov_b64 s[54:55], s[50:51]
	s_cselect_b32 s15, s15, 0
	s_cselect_b32 s14, s19, s14
	s_mov_b64 s[52:53], s[48:49]
	s_cselect_b32 s19, s53, s55
	s_cselect_b32 s22, s52, s54
	s_lshl_b64 s[14:15], s[14:15], 12
	s_add_u32 s14, s22, s14
	s_addc_u32 s15, s19, s15
	global_load_dwordx4 v[68:71], v66, s[14:15]
	global_load_dwordx4 v[72:75], v66, s[14:15] offset:1024
	global_load_dwordx4 v[76:79], v66, s[14:15] offset:2048
	global_load_dwordx4 v[80:83], v66, s[14:15] offset:3072
	s_add_i32 s14, s16, 0xffffc000
	s_cmpk_lt_i32 s16, 0x4000
	s_cselect_b32 s15, s17, 0
	s_cselect_b32 s14, s16, s14
	s_cselect_b32 s19, s53, s55
	s_cselect_b32 s22, s52, s54
	s_lshl_b64 s[14:15], s[14:15], 12
	s_add_u32 s14, s22, s14
	s_addc_u32 s15, s19, s15
	global_load_dwordx4 v[46:49], v66, s[14:15]
	global_load_dwordx4 v[42:45], v66, s[14:15] offset:1024
	global_load_dwordx4 v[38:41], v66, s[14:15] offset:2048
	global_load_dwordx4 v[34:37], v66, s[14:15] offset:3072
	s_add_u32 s14, s16, 1
	s_addc_u32 s15, s17, 0
	s_add_i32 s19, s16, 0xffffc001
	s_cmpk_lt_i32 s14, 0x4000
	s_cselect_b32 s15, s15, 0
	s_cselect_b32 s14, s14, s19
	s_cselect_b32 s19, s53, s55
	s_cselect_b32 s22, s52, s54
	s_lshl_b64 s[14:15], s[14:15], 12
	s_add_u32 s14, s22, s14
	s_addc_u32 s15, s19, s15
	global_load_dwordx4 v[30:33], v66, s[14:15]
	global_load_dwordx4 v[26:29], v66, s[14:15] offset:1024
	global_load_dwordx4 v[22:25], v66, s[14:15] offset:2048
	global_load_dwordx4 v[18:21], v66, s[14:15] offset:3072
	s_add_u32 s14, s16, 2
	s_addc_u32 s15, s17, 0
	s_add_i32 s19, s16, 0xffffc002
	s_cmpk_lt_i32 s14, 0x4000
	s_cselect_b32 s15, s15, 0
	s_cselect_b32 s14, s14, s19
	s_cselect_b32 s19, s53, s55
	s_cselect_b32 s22, s52, s54
	s_lshl_b64 s[14:15], s[14:15], 12
	s_add_u32 s14, s22, s14
	s_addc_u32 s15, s19, s15
	s_waitcnt lgkmcnt(0)
	global_load_dwordx4 v[14:17], v66, s[14:15]
	global_load_dwordx4 v[10:13], v66, s[14:15] offset:1024
	global_load_dwordx4 v[6:9], v66, s[14:15] offset:2048
	global_load_dwordx4 v[2:5], v66, s[14:15] offset:3072
	v_readlane_b32 s56, v252, 11
	v_readlane_b32 s57, v252, 12
	v_readlane_b32 s58, v252, 13
	v_readlane_b32 s59, v252, 14
	v_readlane_b32 s60, v252, 15
	v_readlane_b32 s61, v252, 16
	v_readlane_b32 s62, v252, 17
	v_readlane_b32 s63, v252, 18
	s_waitcnt vmcnt(15)
	v_mul_f32_e32 v56, v69, v69
	v_mul_f32_e32 v57, v71, v71
	s_waitcnt vmcnt(14)
	v_mul_f32_e32 v58, v73, v73
	v_mul_f32_e32 v59, v75, v75
	s_waitcnt vmcnt(13)
	v_mul_f32_e32 v60, v77, v77
	v_mul_f32_e32 v61, v79, v79
	v_fmac_f32_e32 v56, v68, v68
	v_fmac_f32_e32 v57, v70, v70
	v_fmac_f32_e32 v58, v72, v72
	v_fmac_f32_e32 v59, v74, v74
	s_waitcnt vmcnt(12)
	v_mul_f32_e32 v67, v81, v81
	v_mul_f32_e32 v84, v83, v83
	v_fmac_f32_e32 v60, v76, v76
	v_fmac_f32_e32 v61, v78, v78
	v_add_f32_e32 v56, v56, v57
	v_add_f32_e32 v57, v58, v59
	v_fmac_f32_e32 v67, v80, v80
	v_fmac_f32_e32 v84, v82, v82
	v_add_f32_e32 v58, v60, v61
	v_add_f32_e32 v56, v56, v57
	v_add_f32_e32 v59, v67, v84
	v_add_f32_e32 v56, v56, v58
	v_add_f32_e32 v56, v56, v59
	ds_bpermute_b32 v57, v1, v56
	v_lshl_add_u64 v[58:59], s[46:47], 0, v[54:55]
	v_add_co_u32_e32 v60, vcc, s7, v58
	s_waitcnt lgkmcnt(0)
	v_add_f32_e32 v56, v56, v57
	ds_bpermute_b32 v57, v51, v56
	v_addc_co_u32_e32 v61, vcc, 0, v59, vcc
	s_waitcnt lgkmcnt(0)
	v_add_f32_e32 v56, v56, v57
	ds_bpermute_b32 v57, v62, v56
	s_waitcnt lgkmcnt(0)
	v_add_f32_e32 v67, v56, v57
	ds_bpermute_b32 v84, v63, v67
	v_cvt_pk_bf16_f32 v56, v68, v69
	v_cvt_pk_bf16_f32 v68, v72, v73
	v_cvt_pk_bf16_f32 v57, v70, v71
	v_cvt_pk_bf16_f32 v69, v74, v75
	s_waitcnt lgkmcnt(0)
	v_add_f32_e32 v67, v67, v84
	ds_bpermute_b32 v72, v64, v67
	global_store_dwordx2 v[60:61], v[56:57], off sc1
	global_store_dwordx2 v[60:61], v[68:69], off offset:512 sc1
	v_cvt_pk_bf16_f32 v56, v80, v81
	v_cvt_pk_bf16_f32 v57, v82, v83
	v_cvt_pk_bf16_f32 v70, v76, v77
	s_waitcnt lgkmcnt(0)
	v_add_f32_e32 v67, v67, v72
	ds_bpermute_b32 v68, v65, v67
	v_cvt_pk_bf16_f32 v71, v78, v79
	global_store_dwordx2 v[60:61], v[56:57], off offset:1536 sc1
	v_lshl_add_u64 v[56:57], s[46:47], 0, v[52:53]
	global_store_dwordx2 v[60:61], v[70:71], off offset:1024 sc1
	s_and_saveexec_b64 s[14:15], s[0:1]
	s_cbranch_execz .LBB0_144
	s_waitcnt lgkmcnt(0)
	v_add_f32_e32 v67, v67, v68
	v_add_co_u32_e32 v68, vcc, 0x800000, v56
	v_cndmask_b32_e64 v67, 0, v67, s[4:5]
	s_nop 0
	v_addc_co_u32_e32 v69, vcc, 0, v57, vcc
	global_store_dword v[68:69], v67, off sc1
.LBB0_144:
	s_or_b64 exec, exec, s[14:15]
	s_waitcnt vmcnt(15)
	v_mul_f32_e32 v67, v47, v47
	s_waitcnt lgkmcnt(0)
	v_mul_f32_e32 v68, v49, v49
	v_fmac_f32_e32 v67, v46, v46
	v_fmac_f32_e32 v68, v48, v48
	v_add_f32_e32 v67, v67, v68
	s_waitcnt vmcnt(14)
	v_mul_f32_e32 v68, v43, v43
	v_mul_f32_e32 v69, v45, v45
	v_fmac_f32_e32 v68, v42, v42
	v_fmac_f32_e32 v69, v44, v44
	v_add_f32_e32 v68, v68, v69
	v_add_f32_e32 v67, v67, v68
	s_waitcnt vmcnt(13)
	v_mul_f32_e32 v68, v39, v39
	v_mul_f32_e32 v69, v41, v41
	v_fmac_f32_e32 v68, v38, v38
	v_fmac_f32_e32 v69, v40, v40
	v_add_f32_e32 v68, v68, v69
	v_add_f32_e32 v67, v67, v68
	s_waitcnt vmcnt(12)
	v_mul_f32_e32 v68, v35, v35
	v_mul_f32_e32 v69, v37, v37
	v_fmac_f32_e32 v68, v34, v34
	v_fmac_f32_e32 v69, v36, v36
	v_add_f32_e32 v68, v68, v69
	v_add_f32_e32 v67, v67, v68
	ds_bpermute_b32 v68, v1, v67
	v_cvt_pk_bf16_f32 v46, v46, v47
	v_cvt_pk_bf16_f32 v47, v48, v49
	global_store_dwordx2 v[60:61], v[46:47], off offset:2048 sc1
	v_cvt_pk_bf16_f32 v42, v42, v43
	s_waitcnt lgkmcnt(0)
	v_add_f32_e32 v67, v67, v68
	ds_bpermute_b32 v68, v51, v67
	v_cvt_pk_bf16_f32 v43, v44, v45
	v_cvt_pk_bf16_f32 v38, v38, v39
	v_cvt_pk_bf16_f32 v39, v40, v41
	v_cvt_pk_bf16_f32 v34, v34, v35
	s_waitcnt lgkmcnt(0)
	v_add_f32_e32 v67, v67, v68
	ds_bpermute_b32 v68, v62, v67
	v_cvt_pk_bf16_f32 v35, v36, v37
	global_store_dwordx2 v[60:61], v[42:43], off offset:2560 sc1
	global_store_dwordx2 v[60:61], v[38:39], off offset:3072 sc1
	global_store_dwordx2 v[60:61], v[34:35], off offset:3584 sc1
	s_waitcnt lgkmcnt(0)
	v_add_f32_e32 v67, v67, v68
	ds_bpermute_b32 v68, v63, v67
	s_waitcnt lgkmcnt(0)
	v_add_f32_e32 v67, v67, v68
	ds_bpermute_b32 v68, v64, v67
	s_waitcnt lgkmcnt(0)
	v_add_f32_e32 v46, v67, v68
	ds_bpermute_b32 v47, v65, v46
	s_and_saveexec_b64 s[14:15], s[0:1]
	s_cbranch_execz .LBB0_146
	s_waitcnt lgkmcnt(0)
	v_add_f32_e32 v34, v46, v47
	v_cndmask_b32_e64 v36, 0, v34, s[4:5]
	v_add_co_u32_e32 v34, vcc, 0x800000, v56
	s_nop 1
	v_addc_co_u32_e32 v35, vcc, 0, v57, vcc
	global_store_dword v[34:35], v36, off offset:64 sc1
.LBB0_146:
	s_or_b64 exec, exec, s[14:15]
	s_waitcnt vmcnt(15)
	v_mul_f32_e32 v34, v31, v31
	v_mul_f32_e32 v35, v33, v33
	v_fmac_f32_e32 v34, v30, v30
	v_fmac_f32_e32 v35, v32, v32
	v_add_f32_e32 v34, v34, v35
	s_waitcnt vmcnt(14)
	v_mul_f32_e32 v35, v27, v27
	v_mul_f32_e32 v36, v29, v29
	v_fmac_f32_e32 v35, v26, v26
	v_fmac_f32_e32 v36, v28, v28
	v_add_f32_e32 v35, v35, v36
	v_add_f32_e32 v34, v34, v35
	s_waitcnt vmcnt(13)
	v_mul_f32_e32 v35, v23, v23
	v_mul_f32_e32 v36, v25, v25
	v_fmac_f32_e32 v35, v22, v22
	v_fmac_f32_e32 v36, v24, v24
	v_add_f32_e32 v35, v35, v36
	v_add_f32_e32 v34, v34, v35
	s_waitcnt vmcnt(12)
	v_mul_f32_e32 v35, v19, v19
	v_mul_f32_e32 v36, v21, v21
	v_fmac_f32_e32 v35, v18, v18
	v_fmac_f32_e32 v36, v20, v20
	v_add_f32_e32 v35, v35, v36
	v_add_f32_e32 v34, v34, v35
	ds_bpermute_b32 v35, v1, v34
	v_cvt_pk_bf16_f32 v26, v26, v27
	v_cvt_pk_bf16_f32 v27, v28, v29
	v_cvt_pk_bf16_f32 v22, v22, v23
	v_cvt_pk_bf16_f32 v23, v24, v25
	s_waitcnt lgkmcnt(0)
	v_add_f32_e32 v34, v34, v35
	ds_bpermute_b32 v35, v51, v34
	v_cvt_pk_bf16_f32 v18, v18, v19
	v_cvt_pk_bf16_f32 v19, v20, v21
	s_waitcnt lgkmcnt(0)
	v_add_f32_e32 v34, v34, v35
	ds_bpermute_b32 v35, v62, v34
	s_waitcnt lgkmcnt(0)
	v_add_f32_e32 v34, v34, v35
	ds_bpermute_b32 v35, v63, v34
	s_waitcnt lgkmcnt(0)
	v_add_f32_e32 v36, v34, v35
	ds_bpermute_b32 v37, v64, v36
	v_cvt_pk_bf16_f32 v35, v32, v33
	v_cvt_pk_bf16_f32 v34, v30, v31
	v_add_co_u32_e32 v30, vcc, s18, v58
	s_waitcnt lgkmcnt(0)
	v_add_f32_e32 v32, v36, v37
	ds_bpermute_b32 v33, v65, v32
	v_addc_co_u32_e32 v31, vcc, 0, v59, vcc
	global_store_dwordx2 v[30:31], v[34:35], off sc1
	global_store_dwordx2 v[30:31], v[26:27], off offset:512 sc1
	global_store_dwordx2 v[30:31], v[22:23], off offset:1024 sc1
	global_store_dwordx2 v[30:31], v[18:19], off offset:1536 sc1
	s_and_saveexec_b64 s[14:15], s[0:1]
	s_cbranch_execz .LBB0_148
	s_waitcnt lgkmcnt(0)
	v_add_f32_e32 v18, v32, v33
	v_cndmask_b32_e64 v20, 0, v18, s[4:5]
	v_add_co_u32_e32 v18, vcc, 0x800000, v56
	s_nop 1
	v_addc_co_u32_e32 v19, vcc, 0, v57, vcc
	global_store_dword v[18:19], v20, off offset:128 sc1
.LBB0_148:
	s_or_b64 exec, exec, s[14:15]
	s_waitcnt vmcnt(15)
	v_mul_f32_e32 v18, v15, v15
	v_mul_f32_e32 v19, v17, v17
	v_fmac_f32_e32 v18, v14, v14
	v_fmac_f32_e32 v19, v16, v16
	v_add_f32_e32 v18, v18, v19
	s_waitcnt vmcnt(14)
	v_mul_f32_e32 v19, v11, v11
	v_mul_f32_e32 v20, v13, v13
	v_fmac_f32_e32 v19, v10, v10
	v_fmac_f32_e32 v20, v12, v12
	v_add_f32_e32 v19, v19, v20
	v_add_f32_e32 v18, v18, v19
	s_waitcnt vmcnt(13)
	v_mul_f32_e32 v19, v7, v7
	v_mul_f32_e32 v20, v9, v9
	v_fmac_f32_e32 v19, v6, v6
	v_fmac_f32_e32 v20, v8, v8
	v_add_f32_e32 v19, v19, v20
	v_add_f32_e32 v18, v18, v19
	s_waitcnt vmcnt(12)
	v_mul_f32_e32 v19, v3, v3
	v_mul_f32_e32 v20, v5, v5
	v_fmac_f32_e32 v19, v2, v2
	v_fmac_f32_e32 v20, v4, v4
	v_add_f32_e32 v19, v19, v20
	v_add_f32_e32 v18, v18, v19
	ds_bpermute_b32 v19, v1, v18
	v_cvt_pk_bf16_f32 v14, v14, v15
	v_cvt_pk_bf16_f32 v15, v16, v17
	global_store_dwordx2 v[30:31], v[14:15], off offset:2048 sc1
	v_cvt_pk_bf16_f32 v10, v10, v11
	s_waitcnt lgkmcnt(0)
	v_add_f32_e32 v18, v18, v19
	ds_bpermute_b32 v19, v51, v18
	v_cvt_pk_bf16_f32 v11, v12, v13
	v_cvt_pk_bf16_f32 v6, v6, v7
	v_cvt_pk_bf16_f32 v7, v8, v9
	v_cvt_pk_bf16_f32 v2, v2, v3
	s_waitcnt lgkmcnt(0)
	v_add_f32_e32 v18, v18, v19
	ds_bpermute_b32 v19, v62, v18
	v_cvt_pk_bf16_f32 v3, v4, v5
	global_store_dwordx2 v[30:31], v[10:11], off offset:2560 sc1
	global_store_dwordx2 v[30:31], v[6:7], off offset:3072 sc1
	global_store_dwordx2 v[30:31], v[2:3], off offset:3584 sc1
	s_waitcnt lgkmcnt(0)
	v_add_f32_e32 v18, v18, v19
	ds_bpermute_b32 v19, v63, v18
	s_waitcnt lgkmcnt(0)
	v_add_f32_e32 v18, v18, v19
	ds_bpermute_b32 v19, v64, v18
	s_waitcnt lgkmcnt(0)
	v_add_f32_e32 v14, v18, v19
	ds_bpermute_b32 v15, v65, v14
	s_and_saveexec_b64 s[14:15], s[0:1]
	s_cbranch_execz .LBB0_141
	s_waitcnt lgkmcnt(0)
	v_add_f32_e32 v2, v14, v15
	v_cndmask_b32_e64 v4, 0, v2, s[4:5]
	v_add_co_u32_e32 v2, vcc, 0x800000, v56
	s_nop 1
	v_addc_co_u32_e32 v3, vcc, 0, v57, vcc
	global_store_dword v[2:3], v4, off offset:192 sc1
	s_branch .LBB0_141

.LBB0_184:
	s_andn2_saveexec_b64 s[8:9], s[8:9]
	s_cbranch_execz .LBB0_204
	s_mov_b64 s[8:9], exec
	s_nop 0
	buffer_inv sc1
	s_waitcnt lgkmcnt(0)
	s_waitcnt vmcnt(0)
	v_mbcnt_lo_u32_b32 v2, s8, 0
	v_mbcnt_hi_u32_b32 v2, s9, v2
	v_cmp_eq_u32_e32 vcc, 0, v2
	s_and_saveexec_b64 s[10:11], vcc
	s_cbranch_execz .LBB0_187
	s_bcnt1_i32_b64 s8, s[8:9]
	v_mov_b32_e32 v3, 0x7000
	v_mov_b32_e32 v4, s8
	global_atomic_add v3, v3, v4, s[46:47] offset:1024 sc0

.LBB0_208:
	s_waitcnt lgkmcnt(3)
	v_add_f32_e32 v8, 0, v14
	v_add_f32_e32 v8, v8, v15
	s_waitcnt lgkmcnt(2)
	v_add_f32_e32 v8, v8, v12
	v_add_f32_e32 v8, v8, v13
	s_waitcnt lgkmcnt(1)
	v_add_f32_e32 v4, v8, v4
	v_add_f32_e32 v4, v4, v5
	s_waitcnt lgkmcnt(0)
	v_add_f32_e32 v2, v4, v2
	v_add_f32_e32 v4, v2, v3
	v_or_b32_e32 v2, s18, v50
	v_ashrrev_i32_e32 v3, 31, v2
	v_lshl_add_u64 v[2:3], v[2:3], 2, v[16:17]
	global_store_dword v[2:3], v4, off sc1

.LBB0_228:
	s_or_b64 exec, exec, s[14:15]
	v_add_u32_e32 v2, s4, v2
	v_cmp_lt_i32_e32 vcc, s18, v2
	s_waitcnt vmcnt(0)
	global_store_dword v[4:5], v10, off sc1
	s_or_b64 s[12:13], vcc, s[12:13]
	v_lshl_add_u64 v[4:5], v[4:5], 0, s[10:11]
	s_andn2_b64 exec, exec, s[12:13]
	s_cbranch_execz .LBB0_240

.LBB0_279:
	s_andn2_saveexec_b64 s[6:7], s[6:7]
	s_cbranch_execz .LBB0_299
	s_mov_b64 s[6:7], exec
	s_nop 0
	buffer_inv sc1
	s_waitcnt lgkmcnt(0)
	s_waitcnt vmcnt(0)
	v_mbcnt_lo_u32_b32 v2, s6, 0
	v_mbcnt_hi_u32_b32 v2, s7, v2
	v_cmp_eq_u32_e32 vcc, 0, v2
	s_and_saveexec_b64 s[8:9], vcc
	s_cbranch_execz .LBB0_282
	s_bcnt1_i32_b64 s6, s[6:7]
	v_mov_b32_e32 v3, 0x7000
	v_mov_b32_e32 v4, s6
	global_atomic_add v3, v3, v4, s[46:47] offset:1024 sc0
